# v13 plus norm-phase row sums by DPP/permlane-swap butterfly instead of ds_bpermute (bitwise same sums)
# speedup vs baseline: 1.0149x; 1.0081x over previous
.LBB0_504:
	v_pk_mul_f32 v[22:23], v[28:29], v[28:29]
	v_pk_mul_f32 v[24:25], v[26:27], v[26:27]
	v_pk_mul_f32 v[18:19], v[32:33], v[32:33]
	v_pk_mul_f32 v[20:21], v[30:31], v[30:31]
	v_pk_mov_b32 v[38:39], v[24:25], v[22:23] op_sel:[1,0]
	v_mov_b32_e32 v25, v23
	v_pk_add_f32 v[22:23], v[38:39], v[24:25]
	v_pk_mov_b32 v[24:25], v[20:21], v[18:19] op_sel:[1,0]
	v_mov_b32_e32 v21, v19
	v_pk_add_f32 v[18:19], v[24:25], v[20:21]
	v_pk_add_f32 v[22:23], v[22:23], v[22:23] op_sel_hi:[0,1]
	v_pk_add_f32 v[18:19], v[18:19], v[18:19] op_sel_hi:[0,1]
	v_mul_f32_e32 v18, v34, v34
	v_pk_fma_f32 v[20:21], v[34:35], v[34:35], v[18:19] op_sel_hi:[1,1,0]
	v_mul_f32_e32 v18, v36, v36
	v_pk_fma_f32 v[24:25], v[36:37], v[36:37], v[18:19] op_sel_hi:[1,1,0]
	v_mul_f32_e32 v20, v100, v100
	v_mul_f32_e32 v24, v101, v101
	v_mul_f32_e32 v22, v102, v102
	v_mul_f32_e32 v18, v103, v103
	v_pk_add_f32 v[20:21], v[20:21], v[24:25]
	v_pk_add_f32 v[18:19], v[22:23], v[18:19]
	s_nop 0
	v_pk_add_f32 v[18:19], v[20:21], v[18:19]
	s_nop 0
	v_add_f32_e32 v18, v18, v19
	s_nop 1
	v_add_f32_dpp v18, v18, v18 quad_perm:[1,0,3,2] row_mask:0xf bank_mask:0xf
	s_nop 1
	v_add_f32_dpp v18, v18, v18 quad_perm:[2,3,0,1] row_mask:0xf bank_mask:0xf
	s_nop 1
	v_add_f32_dpp v18, v18, v18 row_half_mirror row_mask:0xf bank_mask:0xf
	s_nop 1
	v_add_f32_dpp v18, v18, v18 row_mirror row_mask:0xf bank_mask:0xf
	s_nop 1
	v_mov_b32_e32 v19, v18
	s_nop 1
	v_permlane16_swap_b32_e32 v18, v19
	s_nop 1
	v_add_f32_e32 v18, v18, v19
	s_nop 1
	v_mov_b32_e32 v19, v18
	s_nop 1
	v_permlane32_swap_b32_e32 v18, v19
	s_nop 1
	v_add_f32_e32 v18, v18, v19
	v_fmamk_f32 v18, v18, 0x3a800000, v1
	v_mul_f32_e32 v19, 0x4f800000, v18
	v_cmp_gt_f32_e32 vcc, s56, v18
	s_nop 1
	v_cndmask_b32_e32 v18, v18, v19, vcc
	v_sqrt_f32_e32 v19, v18
	s_nop 0
	v_add_u32_e32 v20, -1, v19
	v_add_u32_e32 v21, 1, v19
	v_fma_f32 v22, -v20, v19, v18
	v_fma_f32 v23, -v21, v19, v18
	v_cmp_ge_f32_e64 s[38:39], 0, v22
	s_nop 1
	v_cndmask_b32_e64 v19, v19, v20, s[38:39]
	v_cmp_lt_f32_e64 s[38:39], 0, v23
	s_nop 1
	v_cndmask_b32_e64 v19, v19, v21, s[38:39]
	v_mul_f32_e32 v20, 0x37800000, v19
	v_cndmask_b32_e32 v19, v19, v20, vcc
	v_cmp_class_f32_e32 vcc, v18, v220
	s_nop 1
	v_cndmask_b32_e32 v18, v19, v18, vcc
	v_div_scale_f32 v19, s[4:5], v18, v18, 1.0
	v_rcp_f32_e32 v20, v19
	v_div_scale_f32 v21, vcc, 1.0, v18, 1.0
	v_fma_f32 v22, -v19, v20, 1.0
	v_fmac_f32_e32 v20, v22, v20
	v_mul_f32_e32 v22, v21, v20
	v_fma_f32 v23, -v19, v22, v21
	v_fmac_f32_e32 v22, v23, v20
	v_fma_f32 v19, -v19, v22, v21
	v_div_fmas_f32 v19, v19, v20, v22
	v_div_fixup_f32 v18, v19, v18, 1.0
	v_pk_mul_f32 v[20:21], v[26:27], v[18:19] op_sel_hi:[1,0]
	v_pk_mul_f32 v[22:23], v[28:29], v[18:19] op_sel_hi:[1,0]
	v_pk_mul_f32 v[24:25], v[30:31], v[18:19] op_sel_hi:[1,0]
	v_pk_mul_f32 v[26:27], v[32:33], v[18:19] op_sel_hi:[1,0]
	s_waitcnt vmcnt(2)
	v_pk_fma_f32 v[22:23], v[2:3], v[22:23], v[56:57]
	v_pk_fma_f32 v[2:3], v[4:5], v[20:21], v[54:55]
	v_pk_fma_f32 v[6:7], v[6:7], v[26:27], v[52:53]
	v_pk_fma_f32 v[4:5], v[8:9], v[24:25], v[50:51]
	v_cvt_pk_bf16_f32 v2, v2, v3
	v_cvt_pk_bf16_f32 v4, v4, v5
	v_cvt_pk_bf16_f32 v5, v6, v7
	v_lshl_add_u64 v[6:7], s[20:21], 0, v[184:185]
	v_add_co_u32_e32 v6, vcc, s46, v6
	v_cvt_pk_bf16_f32 v3, v22, v23
	s_nop 0
	v_addc_co_u32_e32 v7, vcc, 0, v7, vcc
	global_store_dwordx4 v[6:7], v[2:5], off
	v_pk_mul_f32 v[8:9], v[58:59], v[18:19] op_sel_hi:[1,0]
	s_nop 0
	v_pk_mul_f32 v[4:5], v[36:37], v[18:19] op_sel_hi:[1,0]
	v_pk_mul_f32 v[2:3], v[34:35], v[18:19] op_sel_hi:[1,0]
	s_waitcnt vmcnt(1)
	v_pk_fma_f32 v[4:5], v[10:11], v[4:5], v[48:49]
	v_pk_mul_f32 v[10:11], v[60:61], v[18:19] op_sel_hi:[1,0]
	v_pk_fma_f32 v[2:3], v[12:13], v[2:3], v[46:47]
	v_pk_fma_f32 v[10:11], v[14:15], v[10:11], v[44:45]
	v_pk_fma_f32 v[8:9], v[16:17], v[8:9], v[42:43]
	v_cvt_pk_bf16_f32 v2, v2, v3
	v_cvt_pk_bf16_f32 v3, v4, v5
	v_cvt_pk_bf16_f32 v4, v8, v9
	v_cvt_pk_bf16_f32 v5, v10, v11
	global_store_dwordx4 v[6:7], v[2:5], off offset:1024

.LBB0_525:
	s_waitcnt vmcnt(0)
	v_pk_mul_f32 v[6:7], v[16:17], v[16:17]
	v_pk_mul_f32 v[8:9], v[14:15], v[14:15]
	v_pk_mul_f32 v[2:3], v[20:21], v[20:21]
	v_pk_mul_f32 v[4:5], v[18:19], v[18:19]
	v_pk_mov_b32 v[10:11], v[8:9], v[6:7] op_sel:[1,0]
	v_mov_b32_e32 v9, v7
	v_pk_add_f32 v[6:7], v[10:11], v[8:9]
	v_pk_mov_b32 v[8:9], v[4:5], v[2:3] op_sel:[1,0]
	v_mov_b32_e32 v5, v3
	v_pk_add_f32 v[2:3], v[8:9], v[4:5]
	v_pk_add_f32 v[6:7], v[6:7], v[6:7] op_sel_hi:[0,1]
	v_pk_add_f32 v[2:3], v[2:3], v[2:3] op_sel_hi:[0,1]
	v_mul_f32_e32 v2, v22, v22
	v_pk_fma_f32 v[4:5], v[22:23], v[22:23], v[2:3] op_sel_hi:[1,1,0]
	v_mul_f32_e32 v2, v24, v24
	v_pk_fma_f32 v[8:9], v[24:25], v[24:25], v[2:3] op_sel_hi:[1,1,0]
	v_mul_f32_e32 v4, v84, v84
	v_mul_f32_e32 v8, v85, v85
	v_mul_f32_e32 v6, v86, v86
	v_mul_f32_e32 v2, v87, v87
	v_pk_add_f32 v[4:5], v[4:5], v[8:9]
	v_pk_add_f32 v[2:3], v[6:7], v[2:3]
	s_nop 0
	v_pk_add_f32 v[2:3], v[4:5], v[2:3]
	s_nop 0
	v_add_f32_e32 v2, v2, v3
	s_nop 1
	v_add_f32_dpp v2, v2, v2 quad_perm:[1,0,3,2] row_mask:0xf bank_mask:0xf
	s_nop 1
	v_add_f32_dpp v2, v2, v2 quad_perm:[2,3,0,1] row_mask:0xf bank_mask:0xf
	s_nop 1
	v_add_f32_dpp v2, v2, v2 row_half_mirror row_mask:0xf bank_mask:0xf
	s_nop 1
	v_add_f32_dpp v2, v2, v2 row_mirror row_mask:0xf bank_mask:0xf
	s_nop 1
	v_mov_b32_e32 v3, v2
	s_nop 1
	v_permlane16_swap_b32_e32 v2, v3
	s_nop 1
	v_add_f32_e32 v2, v2, v3
	s_nop 1
	v_mov_b32_e32 v3, v2
	s_nop 1
	v_permlane32_swap_b32_e32 v2, v3
	s_nop 1
	v_add_f32_e32 v2, v2, v3
	v_fmamk_f32 v2, v2, 0x3a800000, v1
	v_mul_f32_e32 v3, 0x4f800000, v2
	v_cmp_gt_f32_e32 vcc, s56, v2
	s_nop 1
	v_cndmask_b32_e32 v4, v2, v3, vcc
	v_sqrt_f32_e32 v5, v4
	v_pk_add_f32 v[2:3], v[78:79], 1.0 op_sel_hi:[1,0]
	v_add_u32_e32 v6, -1, v5
	v_add_u32_e32 v7, 1, v5
	v_fma_f32 v8, -v6, v5, v4
	v_fma_f32 v9, -v7, v5, v4
	v_cmp_ge_f32_e64 s[38:39], 0, v8
	s_nop 1
	v_cndmask_b32_e64 v5, v5, v6, s[38:39]
	v_cmp_lt_f32_e64 s[38:39], 0, v9
	s_nop 1
	v_cndmask_b32_e64 v5, v5, v7, s[38:39]
	v_mul_f32_e32 v6, 0x37800000, v5
	v_cndmask_b32_e32 v5, v5, v6, vcc
	v_cmp_class_f32_e32 vcc, v4, v220
	s_nop 1
	v_cndmask_b32_e32 v6, v5, v4, vcc
	v_div_scale_f32 v7, s[4:5], v6, v6, 1.0
	v_rcp_f32_e32 v8, v7
	v_div_scale_f32 v9, vcc, 1.0, v6, 1.0
	v_pk_add_f32 v[4:5], v[76:77], 1.0 op_sel_hi:[1,0]
	v_fma_f32 v10, -v7, v8, 1.0
	v_fmac_f32_e32 v8, v10, v8
	v_mul_f32_e32 v10, v9, v8
	v_fma_f32 v11, -v7, v10, v9
	v_fmac_f32_e32 v10, v11, v8
	v_fma_f32 v7, -v7, v10, v9
	v_div_fmas_f32 v7, v7, v8, v10
	v_div_fixup_f32 v38, v7, v6, 1.0
	v_pk_mul_f32 v[8:9], v[16:17], v[38:39] op_sel_hi:[1,0]
	v_pk_mul_f32 v[6:7], v[14:15], v[38:39] op_sel_hi:[1,0]
	v_pk_fma_f32 v[12:13], v[2:3], v[8:9], v[56:57]
	v_pk_mul_f32 v[14:15], v[18:19], v[38:39] op_sel_hi:[1,0]
	v_pk_add_f32 v[8:9], v[72:73], 1.0 op_sel_hi:[1,0]
	v_pk_fma_f32 v[10:11], v[4:5], v[6:7], v[54:55]
	v_pk_fma_f32 v[14:15], v[8:9], v[14:15], v[50:51]
	v_pk_mul_f32 v[16:17], v[20:21], v[38:39] op_sel_hi:[1,0]
	v_pk_add_f32 v[6:7], v[74:75], 1.0 op_sel_hi:[1,0]
	v_cvt_pk_bf16_f32 v10, v10, v11
	v_cvt_pk_bf16_f32 v11, v12, v13
	v_cvt_pk_bf16_f32 v12, v14, v15
	v_lshl_add_u64 v[14:15], s[10:11], 0, v[184:185]
	v_pk_fma_f32 v[16:17], v[6:7], v[16:17], v[52:53]
	v_add_co_u32_e32 v40, vcc, s46, v14
	v_cvt_pk_bf16_f32 v13, v16, v17
	s_nop 0
	v_addc_co_u32_e32 v41, vcc, 0, v15, vcc
	global_store_dwordx4 v[40:41], v[10:13], off
	v_pk_mul_f32 v[14:15], v[22:23], v[38:39] op_sel_hi:[1,0]
	v_pk_mul_f32 v[16:17], v[24:25], v[38:39] op_sel_hi:[1,0]
	v_pk_add_f32 v[10:11], v[70:71], 1.0 op_sel_hi:[1,0]
	v_pk_add_f32 v[12:13], v[68:69], 1.0 op_sel_hi:[1,0]
	v_pk_fma_f32 v[20:21], v[10:11], v[16:17], v[48:49]
	v_pk_fma_f32 v[18:19], v[12:13], v[14:15], v[46:47]
	v_pk_mul_f32 v[22:23], v[80:81], v[38:39] op_sel_hi:[1,0]
	v_pk_mul_f32 v[24:25], v[82:83], v[38:39] op_sel_hi:[1,0]
	v_pk_add_f32 v[14:15], v[64:65], 1.0 op_sel_hi:[1,0]
	v_pk_add_f32 v[16:17], v[62:63], 1.0 op_sel_hi:[1,0]
	v_pk_fma_f32 v[24:25], v[14:15], v[24:25], v[44:45]
	v_pk_fma_f32 v[22:23], v[16:17], v[22:23], v[42:43]
	v_cvt_pk_bf16_f32 v18, v18, v19
	v_cvt_pk_bf16_f32 v19, v20, v21
	v_cvt_pk_bf16_f32 v20, v22, v23
	v_cvt_pk_bf16_f32 v21, v24, v25
	s_andn2_b64 vcc, exec, s[40:41]
	global_store_dwordx4 v[40:41], v[18:21], off offset:1024
	s_cbranch_vccnz .LBB0_505
	s_min_i32 s4, s30, 0x4000
	s_ashr_i32 s4, s4, 12
	s_cmp_eq_u32 s4, s31
	s_cbranch_scc1 .LBB0_504
	s_mulk_i32 s4, 0x4800
	s_ashr_i32 s5, s4, 31
	s_lshl_b64 s[4:5], s[4:5], 2
	s_add_u32 s4, s16, s4
	s_addc_u32 s5, s17, s5
	s_add_u32 s28, s4, 0x1000
	s_addc_u32 s29, s5, 0
	global_load_dwordx4 v[4:7], v147, s[28:29]
	global_load_dwordx4 v[8:11], v147, s[28:29] offset:16
	global_load_dwordx4 v[16:19], v146, s[28:29] offset:16
	global_load_dwordx4 v[12:15], v146, s[28:29]
	global_load_dwordx4 v[50:53], v147, s[4:5] offset:16
	global_load_dwordx4 v[54:57], v147, s[4:5]
	global_load_dwordx4 v[42:45], v147, s[4:5] offset:2064
	global_load_dwordx4 v[46:49], v147, s[4:5] offset:2048
	s_waitcnt vmcnt(7)
	v_pk_add_f32 v[2:3], v[6:7], 1.0 op_sel_hi:[1,0]
	v_pk_add_f32 v[4:5], v[4:5], 1.0 op_sel_hi:[1,0]
	s_waitcnt vmcnt(6)
	v_pk_add_f32 v[6:7], v[10:11], 1.0 op_sel_hi:[1,0]
	v_pk_add_f32 v[8:9], v[8:9], 1.0 op_sel_hi:[1,0]
	s_waitcnt vmcnt(4)
	v_pk_add_f32 v[10:11], v[14:15], 1.0 op_sel_hi:[1,0]
	v_pk_add_f32 v[12:13], v[12:13], 1.0 op_sel_hi:[1,0]
	v_pk_add_f32 v[14:15], v[18:19], 1.0 op_sel_hi:[1,0]
	v_pk_add_f32 v[16:17], v[16:17], 1.0 op_sel_hi:[1,0]
	s_branch .LBB0_504
